# FoX attention tile body: all eight K fragment LDS reads of the QK part issued up front (four into fresh registers) behind counted waits
# baseline (speedup 1.0000x reference)
; #define MFMA(a, b, c) __builtin_amdgcn_mfma_f32_16x16x32_bf16((a), (b), (c), 0, 0, 0)
; template <int DK, bool BIAS> ...
;     ...
; #pragma unroll
;       for (int ks = 0; ks < KS; ++ks)
; #pragma unroll
;         for (int kt = 0; kt < 4; ++kt) { const bf16x8 ak = *(const bf16x8*)(Ksm + (buf * 64 + 16 * kt + fr) * KST + 32 * ks + 8 * fq);
; #pragma unroll
;           for (int qi = 0; qi < 2; ++qi) S[kt][qi] = MFMA(ak, qf[qi][ks], S[kt][qi]); }
;       bf16x8 pf[2][2];
;       if (64 * j + 63 > q0 + 32 * w) {
; #pragma unroll
;         for (int qi = 0; qi < 2; ++qi) { const int qg = q0 + 32 * w + 16 * qi + fr;
; #pragma unroll
;           for (int kt = 0; kt < 4; ++kt)
; #pragma unroll
;             for (int r = 0; r < 4; ++r) { const int kg = 64 * j + 16 * kt + 4 * fq + r; if (kg > qg) S[kt][qi][r] = -1e30f; } }
;       }
.LBB0_1772:
	s_and_saveexec_b64 s[0:1], s[8:9]
	s_cbranch_execz .LBB0_1778
	v_cmp_le_i32_e32 vcc, s38, v167
	s_and_saveexec_b64 s[94:95], vcc
	s_cbranch_execz .LBB0_1777
	ds_read_b128 v[80:83], v169 offset:4608
	ds_read_b128 v[64:67], v169
	ds_read_b128 v[84:87], v169 offset:64
	ds_read_b128 v[72:75], v169 offset:2304
	ds_read_b128 v[210:213], v169 offset:6912
	ds_read_b128 v[214:217], v169 offset:2368
	ds_read_b128 v[218:221], v169 offset:6976
	ds_read_b128 v[222:225], v169 offset:4672
	s_add_i32 s18, s38, 63
	v_cmp_gt_i32_e32 vcc, s18, v127
	s_waitcnt lgkmcnt(7)
	v_mfma_f32_16x16x32_bf16 v[90:93], v[80:83], v[4:7], 0
	v_mfma_f32_16x16x32_bf16 v[94:97], v[80:83], v[12:15], 0
	s_waitcnt lgkmcnt(6)
	v_mfma_f32_16x16x32_bf16 v[68:71], v[64:67], v[4:7], 0
	s_waitcnt lgkmcnt(3)
	v_mfma_f32_16x16x32_bf16 v[116:119], v[210:213], v[4:7], 0
	v_mfma_f32_16x16x32_bf16 v[120:123], v[210:213], v[12:15], 0
	v_mfma_f32_16x16x32_bf16 v[80:83], v[84:87], v[0:3], v[68:71]
	v_mfma_f32_16x16x32_bf16 v[64:67], v[64:67], v[12:15], 0
	v_mfma_f32_16x16x32_bf16 v[76:79], v[72:75], v[4:7], 0
	v_mfma_f32_16x16x32_bf16 v[72:75], v[72:75], v[12:15], 0
	v_mfma_f32_16x16x32_bf16 v[64:67], v[84:87], v[8:11], v[64:67]
	s_waitcnt lgkmcnt(2)
	v_mfma_f32_16x16x32_bf16 v[86:89], v[214:217], v[0:3], v[76:79]
	v_mfma_f32_16x16x32_bf16 v[68:71], v[214:217], v[8:11], v[72:75]
	s_waitcnt lgkmcnt(0)
	v_mfma_f32_16x16x32_bf16 v[90:93], v[222:225], v[0:3], v[90:93]
	v_mfma_f32_16x16x32_bf16 v[72:75], v[222:225], v[8:11], v[94:97]
	v_mfma_f32_16x16x32_bf16 v[94:97], v[218:221], v[0:3], v[116:119]
	v_mfma_f32_16x16x32_bf16 v[76:79], v[218:221], v[8:11], v[120:123]
	s_and_saveexec_b64 s[18:19], vcc
	s_cbranch_execz .LBB0_1776
	v_add_u32_e32 v85, s38, v103
	v_mov_b32_e32 v84, s30
	v_cmp_gt_i32_e32 vcc, v85, v158
	v_add_u32_e32 v113, 2, v85
	v_add_u32_e32 v115, 3, v85
	v_cndmask_b32_e32 v84, v80, v84, vcc
	v_cmp_lt_i32_e32 vcc, v85, v158
	v_add_u32_e32 v116, 16, v85
	v_add_u32_e32 v117, 17, v85
	v_cndmask_b32_e32 v80, v84, v80, vcc
	v_cndmask_b32_e32 v81, v193, v81, vcc
	v_cmp_le_i32_e32 vcc, v113, v158
	v_mov_b32_e32 v84, s30
	v_add_u32_e32 v118, 18, v85
	v_cndmask_b32_e32 v82, v193, v82, vcc
	v_cmp_le_i32_e32 vcc, v115, v158
	v_add_u32_e32 v119, 19, v85
	v_add_u32_e32 v120, 32, v85
	v_cndmask_b32_e32 v83, v193, v83, vcc
	v_cmp_gt_i32_e32 vcc, v116, v158
	v_add_u32_e32 v121, 33, v85
	v_add_u32_e32 v122, 34, v85
	v_cndmask_b32_e32 v86, v86, v84, vcc
	v_cmp_le_i32_e32 vcc, v117, v158
	v_add_u32_e32 v123, 35, v85
	v_add_u32_e32 v124, 48, v85
	v_cndmask_b32_e32 v87, v193, v87, vcc
	v_cmp_le_i32_e32 vcc, v118, v158
	v_add_u32_e32 v125, 49, v85
	v_add_u32_e32 v126, 50, v85
	v_cndmask_b32_e32 v88, v193, v88, vcc
	v_cmp_le_i32_e32 vcc, v119, v158
	v_add_u32_e32 v131, 51, v85
	s_nop 0
	v_cndmask_b32_e32 v89, v193, v89, vcc
	v_cmp_gt_i32_e32 vcc, v120, v158
	v_cmp_le_i32_e64 s[100:101], v121, v158
	s_nop 0
	v_cndmask_b32_e32 v90, v90, v84, vcc
	v_cndmask_b32_e64 v91, v193, v91, s[100:101]
	v_cmp_le_i32_e32 vcc, v122, v158
	v_cmp_le_i32_e64 s[100:101], v123, v158
	s_nop 0
	v_cndmask_b32_e32 v92, v193, v92, vcc
	v_cndmask_b32_e64 v93, v193, v93, s[100:101]
	v_cmp_gt_i32_e32 vcc, v124, v158
	v_cmp_le_i32_e64 s[100:101], v125, v158
	s_nop 0
	v_cndmask_b32_e32 v94, v94, v84, vcc
	v_cndmask_b32_e64 v95, v193, v95, s[100:101]
	v_cmp_le_i32_e32 vcc, v126, v158
	v_cmp_le_i32_e64 s[100:101], v131, v158
	s_nop 0
	v_cndmask_b32_e32 v96, v193, v96, vcc
	v_cndmask_b32_e64 v97, v193, v97, s[100:101]
	v_cmp_gt_i32_e32 vcc, v85, v105
	s_nop 1
	v_cndmask_b32_e32 v84, v64, v84, vcc
	v_cmp_lt_i32_e32 vcc, v85, v105
	s_nop 1
	v_cndmask_b32_e32 v64, v84, v64, vcc
	v_cndmask_b32_e32 v65, v193, v65, vcc
	v_cmp_le_i32_e32 vcc, v113, v105
	v_mov_b32_e32 v84, s30
	s_nop 0
	v_cndmask_b32_e32 v66, v193, v66, vcc
	v_cmp_le_i32_e32 vcc, v115, v105
	v_cmp_gt_i32_e64 s[100:101], v116, v105
	s_nop 0
	v_cndmask_b32_e32 v67, v193, v67, vcc
	v_cndmask_b32_e64 v68, v68, v84, s[100:101]
	v_cmp_le_i32_e32 vcc, v117, v105
	v_cmp_le_i32_e64 s[100:101], v118, v105
	s_nop 0
	v_cndmask_b32_e32 v69, v193, v69, vcc
	v_cndmask_b32_e64 v70, v193, v70, s[100:101]
	v_cmp_le_i32_e32 vcc, v119, v105
	v_cmp_gt_i32_e64 s[100:101], v120, v105
	s_nop 0
	v_cndmask_b32_e32 v71, v193, v71, vcc
	v_cndmask_b32_e64 v72, v72, v84, s[100:101]
	v_cmp_le_i32_e32 vcc, v121, v105
	v_cmp_le_i32_e64 s[100:101], v122, v105
	s_nop 0
	v_cndmask_b32_e32 v73, v193, v73, vcc
	v_cndmask_b32_e64 v74, v193, v74, s[100:101]
	v_cmp_le_i32_e32 vcc, v123, v105
	v_cmp_gt_i32_e64 s[100:101], v124, v105
	s_nop 0
	v_cndmask_b32_e32 v75, v193, v75, vcc
	v_cndmask_b32_e64 v76, v76, v84, s[100:101]
	v_cmp_le_i32_e32 vcc, v125, v105
	v_cmp_le_i32_e64 s[100:101], v126, v105
	s_nop 0
	v_cndmask_b32_e32 v77, v193, v77, vcc
	v_cndmask_b32_e64 v78, v193, v78, s[100:101]
	v_cmp_le_i32_e32 vcc, v131, v105
	s_nop 1
	v_cndmask_b32_e32 v79, v193, v79, vcc

; #define MFMA(a, b, c) __builtin_amdgcn_mfma_f32_16x16x32_bf16((a), (b), (c), 0, 0, 0)
; template <int DK, bool BIAS> ...
;     ...
; #pragma unroll
;       for (int ks = 0; ks < KS; ++ks)
; #pragma unroll
;         for (int kt = 0; kt < 4; ++kt) { const bf16x8 ak = *(const bf16x8*)(Ksm + (buf * 64 + 16 * kt + fr) * KST + 32 * ks + 8 * fq);
; #pragma unroll
;           for (int qi = 0; qi < 2; ++qi) S[kt][qi] = MFMA(ak, qf[qi][ks], S[kt][qi]); }
;       bf16x8 pf[2][2];
;       if (64 * j + 63 > q0 + 32 * w) {
; #pragma unroll
;         for (int qi = 0; qi < 2; ++qi) { const int qg = q0 + 32 * w + 16 * qi + fr;
; #pragma unroll
;           for (int kt = 0; kt < 4; ++kt)
; #pragma unroll
;             for (int r = 0; r < 4; ++r) { const int kg = 64 * j + 16 * kt + 4 * fq + r; if (kg > qg) S[kt][qi][r] = -1e30f; } }
;       }
.LBB0_1793:
	s_and_saveexec_b64 s[0:1], s[8:9]
	s_cbranch_execz .LBB0_1799
	s_add_i32 s18, s38, 64
	v_cmp_le_i32_e32 vcc, s18, v167
	s_and_saveexec_b64 s[92:93], vcc
	s_cbranch_execz .LBB0_1798
	ds_read_b128 v[80:83], v169 offset:13824
	ds_read_b128 v[64:67], v169 offset:9216
	ds_read_b128 v[84:87], v169 offset:9280
	ds_read_b128 v[72:75], v169 offset:11520
	ds_read_b128 v[210:213], v169 offset:16128
	ds_read_b128 v[214:217], v169 offset:11584
	ds_read_b128 v[218:221], v169 offset:16192
	ds_read_b128 v[222:225], v169 offset:13888
	s_add_i32 s18, s38, 0x7f
	v_cmp_gt_i32_e32 vcc, s18, v127
	s_waitcnt lgkmcnt(7)
	v_mfma_f32_16x16x32_bf16 v[90:93], v[80:83], v[4:7], 0
	v_mfma_f32_16x16x32_bf16 v[94:97], v[80:83], v[12:15], 0
	s_waitcnt lgkmcnt(6)
	v_mfma_f32_16x16x32_bf16 v[68:71], v[64:67], v[4:7], 0
	s_waitcnt lgkmcnt(3)
	v_mfma_f32_16x16x32_bf16 v[116:119], v[210:213], v[4:7], 0
	v_mfma_f32_16x16x32_bf16 v[120:123], v[210:213], v[12:15], 0
	v_mfma_f32_16x16x32_bf16 v[80:83], v[84:87], v[0:3], v[68:71]
	v_mfma_f32_16x16x32_bf16 v[64:67], v[64:67], v[12:15], 0
	v_mfma_f32_16x16x32_bf16 v[76:79], v[72:75], v[4:7], 0
	v_mfma_f32_16x16x32_bf16 v[72:75], v[72:75], v[12:15], 0
	v_mfma_f32_16x16x32_bf16 v[64:67], v[84:87], v[8:11], v[64:67]
	s_waitcnt lgkmcnt(2)
	v_mfma_f32_16x16x32_bf16 v[86:89], v[214:217], v[0:3], v[76:79]
	v_mfma_f32_16x16x32_bf16 v[68:71], v[214:217], v[8:11], v[72:75]
	s_waitcnt lgkmcnt(0)
	v_mfma_f32_16x16x32_bf16 v[90:93], v[222:225], v[0:3], v[90:93]
	v_mfma_f32_16x16x32_bf16 v[72:75], v[222:225], v[8:11], v[94:97]
	v_mfma_f32_16x16x32_bf16 v[94:97], v[218:221], v[0:3], v[116:119]
	v_mfma_f32_16x16x32_bf16 v[76:79], v[218:221], v[8:11], v[120:123]
	s_and_saveexec_b64 s[18:19], vcc
	s_cbranch_execz .LBB0_1797
	v_add_u32_e32 v85, s38, v103
	v_add_u32_e32 v113, 64, v85
	v_mov_b32_e32 v84, s30
	v_cmp_gt_i32_e32 vcc, v113, v158
	v_add_u32_e32 v115, 0x42, v85
	v_add_u32_e32 v116, 0x43, v85
	v_cndmask_b32_e32 v84, v80, v84, vcc
	v_cmp_lt_i32_e32 vcc, v113, v158
	v_add_u32_e32 v117, 0x50, v85
	v_add_u32_e32 v118, 0x51, v85
	v_cndmask_b32_e32 v80, v84, v80, vcc
	v_cndmask_b32_e32 v81, v193, v81, vcc
	v_cmp_le_i32_e32 vcc, v115, v158
	v_mov_b32_e32 v84, s30
	v_add_u32_e32 v119, 0x52, v85
	v_cndmask_b32_e32 v82, v193, v82, vcc
	v_cmp_le_i32_e32 vcc, v116, v158
	v_add_u32_e32 v120, 0x53, v85
	v_add_u32_e32 v121, 0x60, v85
	v_cndmask_b32_e32 v83, v193, v83, vcc
	v_cmp_gt_i32_e32 vcc, v117, v158
	v_add_u32_e32 v122, 0x61, v85
	v_add_u32_e32 v123, 0x62, v85
	v_cndmask_b32_e32 v86, v86, v84, vcc
	v_cmp_le_i32_e32 vcc, v118, v158
	v_add_u32_e32 v124, 0x63, v85
	v_add_u32_e32 v125, 0x70, v85
	v_cndmask_b32_e32 v87, v193, v87, vcc
	v_cmp_le_i32_e32 vcc, v119, v158
	v_add_u32_e32 v126, 0x71, v85
	v_add_u32_e32 v131, 0x72, v85
	v_cndmask_b32_e32 v88, v193, v88, vcc
	v_cmp_le_i32_e32 vcc, v120, v158
	v_add_u32_e32 v85, 0x73, v85
	s_nop 0
	v_cndmask_b32_e32 v89, v193, v89, vcc
	v_cmp_gt_i32_e32 vcc, v121, v158
	v_cmp_le_i32_e64 s[100:101], v122, v158
	s_nop 0
	v_cndmask_b32_e32 v90, v90, v84, vcc
	v_cndmask_b32_e64 v91, v193, v91, s[100:101]
	v_cmp_le_i32_e32 vcc, v123, v158
	v_cmp_le_i32_e64 s[100:101], v124, v158
	s_nop 0
	v_cndmask_b32_e32 v92, v193, v92, vcc
	v_cndmask_b32_e64 v93, v193, v93, s[100:101]
	v_cmp_gt_i32_e32 vcc, v125, v158
	v_cmp_le_i32_e64 s[100:101], v126, v158
	s_nop 0
	v_cndmask_b32_e32 v94, v94, v84, vcc
	v_cndmask_b32_e64 v95, v193, v95, s[100:101]
	v_cmp_le_i32_e32 vcc, v131, v158
	v_cmp_le_i32_e64 s[100:101], v85, v158
	s_nop 0
	v_cndmask_b32_e32 v96, v193, v96, vcc
	v_cndmask_b32_e64 v97, v193, v97, s[100:101]
	v_cmp_gt_i32_e32 vcc, v113, v105
	s_nop 1
	v_cndmask_b32_e32 v84, v64, v84, vcc
	v_cmp_lt_i32_e32 vcc, v113, v105
	s_nop 1
	v_cndmask_b32_e32 v64, v84, v64, vcc
	v_cndmask_b32_e32 v65, v193, v65, vcc
	v_cmp_le_i32_e32 vcc, v115, v105
	v_mov_b32_e32 v84, s30
	s_nop 0
	v_cndmask_b32_e32 v66, v193, v66, vcc
	v_cmp_le_i32_e32 vcc, v116, v105
	v_cmp_gt_i32_e64 s[100:101], v117, v105
	s_nop 0
	v_cndmask_b32_e32 v67, v193, v67, vcc
	v_cndmask_b32_e64 v68, v68, v84, s[100:101]
	v_cmp_le_i32_e32 vcc, v118, v105
	v_cmp_le_i32_e64 s[100:101], v119, v105
	s_nop 0
	v_cndmask_b32_e32 v69, v193, v69, vcc
	v_cndmask_b32_e64 v70, v193, v70, s[100:101]
	v_cmp_le_i32_e32 vcc, v120, v105
	v_cmp_gt_i32_e64 s[100:101], v121, v105
	s_nop 0
	v_cndmask_b32_e32 v71, v193, v71, vcc
	v_cndmask_b32_e64 v72, v72, v84, s[100:101]
	v_cmp_le_i32_e32 vcc, v122, v105
	v_cmp_le_i32_e64 s[100:101], v123, v105
	s_nop 0
	v_cndmask_b32_e32 v73, v193, v73, vcc
	v_cndmask_b32_e64 v74, v193, v74, s[100:101]
	v_cmp_le_i32_e32 vcc, v124, v105
	v_cmp_gt_i32_e64 s[100:101], v125, v105
	s_nop 0
	v_cndmask_b32_e32 v75, v193, v75, vcc
	v_cndmask_b32_e64 v76, v76, v84, s[100:101]
	v_cmp_le_i32_e32 vcc, v126, v105
	v_cmp_le_i32_e64 s[100:101], v131, v105
	s_nop 0
	v_cndmask_b32_e32 v77, v193, v77, vcc
	v_cndmask_b32_e64 v78, v193, v78, s[100:101]
	v_cmp_le_i32_e32 vcc, v85, v105
	s_nop 1
	v_cndmask_b32_e32 v79, v193, v79, vcc
